# same as previous with the MFMA-to-VALU distance before the interleaved exps padded to the full 12 wait states
# baseline (speedup 1.0000x reference)
; __device__ __forceinline__ void at_qk_half(const bool ONLINE, const bool act, const LAS unsigned char* kp, u32x4& pfa, u32x4& pfb, const char* pga, const char* pgb, const bf16x8 (&qf)[4], int q, int q0, int kbase, int hh, float& mrun, f32x16 (&O)[4], f32x16& L, bf16x8 (&pf)[4]) {
;     __builtin_amdgcn_s_setprio(3);
;     bf16x8 kf[8];
; #pragma unroll
;     for (int s = 0; s < 4; ++s) { kf[2 * s] = *(const LAS bf16x8*)(kp + 32 * s); kf[2 * s + 1] = *(const LAS bf16x8*)(kp + 32 * AT_ROWB + 32 * s); }
;     __builtin_amdgcn_sched_barrier(0);
;     pfa = *(const u32x4*)pga; pfb = *(const u32x4*)pgb;
;     __builtin_amdgcn_sched_barrier(0);
;     if (!act) { __builtin_amdgcn_s_setprio(0); return; }
;     f32x16 s0, s1;
; #pragma unroll
;     for (int i = 0; i < 16; ++i) { s0[i] = 0.f; s1[i] = 0.f; }
; #pragma unroll
;     for (int s = 0; s < 4; ++s) { s0 = MFMA32(kf[2 * s], qf[s], s0); s1 = MFMA32(kf[2 * s + 1], qf[s], s1); }
;     __builtin_amdgcn_s_setprio(0);
;     if (kbase + 63 > q0) {
;         const int kb = kbase + 4 * hh;
; #pragma unroll
;         for (int i = 0; i < 16; ++i) { const int kv = kb + (i & 3) + 8 * (i >> 2); if (kv > q) s0[i] = -INFINITY; if (kv + 32 > q) s1[i] = -INFINITY; }
;     }
;     if (ONLINE) {
; #pragma unroll
;         for (int i = 0; i < 16; ++i) { s0[i] -= mrun; s1[i] -= mrun; }
;         float mx = fmaxf(s0[0], s1[0]);
; #pragma unroll
;         for (int i = 1; i < 16; ++i) mx = at_max3(mx, s0[i], s1[i]);
;         mx = half_swap_max(mx);
;         if (__builtin_amdgcn_ballot_w64(mx > 8.f) != 0ull) {
;             const float d = fmaxf(mx, 0.f); const float alpha = __builtin_amdgcn_exp2f(-d); mrun += d;
; #pragma unroll
;             for (int e = 0; e < 4; ++e)
; #pragma unroll
;                 for (int i = 0; i < 16; ++i) O[e][i] *= alpha;
; __device__ __forceinline__ void attn_item(LAS unsigned char* lds, const bf16_t* Q, const bf16_t* Kb, const bf16_t* VT, bf16_t* aout, const float* subg, float lam, float omli, float kbound, int head, int qb) {
;     ...
;             __syncthreads();
;             __builtin_amdgcn_s_setprio(3);
;             { const int jc_ = (j + 2) < ntm1 ? (j + 2) : ntm1; const size_t ko_ = (size_t)jc_ * 8192; const char* pga = bK1 + ko_ + koff; const char* pgb = bK2 + ko_ + koff;
;               at_qk_half(online, kbase <= qmax, stg + kfo, ks0, ks1, pga, pgb, qf, q, q0, kbase, hh, mrun, O, L, pf); }
.Lmy_wj1:
	v_add_u32_e32 v232, s56, v212
	s_bitcmp1_b32 s45, 0
	s_cselect_b32 s53, 0x4800, 0
	s_sub_i32 s57, s1, 63
	s_waitcnt lgkmcnt(0)
	s_barrier
	s_setprio 3
	s_add_i32 s45, s45, 2
	s_min_i32 s58, s45, s41
	s_lshl_b64 s[54:55], s[58:59], 13
	v_lshl_add_u64 v[100:101], v[204:205], 0, s[54:55]
	v_lshl_add_u64 v[102:103], v[206:207], 0, s[54:55]
	s_cmp_gt_i32 s57, s40
	v_add_u32_e32 v104, s53, v230
	s_setprio 3
	ds_read_b128 v[96:99], v104
	ds_read_b128 v[166:169], v104 offset:32
	ds_read_b128 v[162:165], v104 offset:64
	ds_read_b128 v[154:157], v104 offset:96
	ds_read_b128 v[178:181], v104 offset:4608
	ds_read_b128 v[170:173], v104 offset:4640
	ds_read_b128 v[174:177], v104 offset:4672
	ds_read_b128 v[158:161], v104 offset:4704
	global_load_dwordx4 v[142:145], v[100:101], off
	global_load_dwordx4 v[138:141], v[102:103], off
	s_cbranch_scc1 .LBB0_304
	s_cmp_le_i32 s1, s33
	s_cbranch_scc0 .Lmy_slow1
	s_andn2_b64 vcc, exec, s[64:65]
	s_cbranch_vccz .Lmy_slow1
	s_waitcnt lgkmcnt(7)
	v_mfma_f32_32x32x16_bf16 v[96:111], v[96:99], v[126:129], 0
	s_waitcnt lgkmcnt(6)
	v_mfma_f32_32x32x16_bf16 v[96:111], v[166:169], v[122:125], v[96:111]
	s_waitcnt lgkmcnt(5)
	v_mfma_f32_32x32x16_bf16 v[96:111], v[162:165], v[118:121], v[96:111]
	s_waitcnt lgkmcnt(4)
	v_mfma_f32_32x32x16_bf16 v[96:111], v[154:157], v[114:117], v[96:111]
	s_waitcnt lgkmcnt(3)
	v_mfma_f32_32x32x16_bf16 v[80:95], v[178:181], v[126:129], 0
	s_waitcnt lgkmcnt(2)
	v_mfma_f32_32x32x16_bf16 v[80:95], v[170:173], v[122:125], v[80:95]
	s_nop 8
	v_exp_f32_e32 v96, v96
	v_exp_f32_e32 v97, v97
	v_exp_f32_e32 v98, v98
	v_exp_f32_e32 v99, v99
	s_waitcnt lgkmcnt(1)
	v_mfma_f32_32x32x16_bf16 v[80:95], v[174:177], v[118:121], v[80:95]
	v_exp_f32_e32 v100, v100
	v_exp_f32_e32 v101, v101
	v_exp_f32_e32 v102, v102
	v_exp_f32_e32 v103, v103
	s_waitcnt lgkmcnt(0)
	v_mfma_f32_32x32x16_bf16 v[80:95], v[158:161], v[114:117], v[80:95]
	s_setprio 0
	v_exp_f32_e32 v104, v104
	v_exp_f32_e32 v105, v105
	v_exp_f32_e32 v106, v106
	v_exp_f32_e32 v107, v107
	v_exp_f32_e32 v108, v108
	v_exp_f32_e32 v109, v109
	v_exp_f32_e32 v110, v110
	v_exp_f32_e32 v111, v111
	s_nop 3
	v_exp_f32_e32 v154, v80
	v_exp_f32_e32 v155, v81
	v_exp_f32_e32 v156, v82
	v_exp_f32_e32 v157, v83
	v_exp_f32_e32 v158, v84
	v_exp_f32_e32 v159, v85
	v_exp_f32_e32 v160, v86
	v_exp_f32_e32 v161, v87
	v_exp_f32_e32 v162, v88
	v_exp_f32_e32 v163, v89
	v_exp_f32_e32 v164, v90
	v_exp_f32_e32 v165, v91
	v_exp_f32_e32 v166, v92
	v_exp_f32_e32 v167, v93
	v_exp_f32_e32 v168, v94
	v_exp_f32_e32 v169, v95
	v_cvt_pk_bf16_f32 v80, v96, v97
	v_cvt_pk_bf16_f32 v81, v98, v99
	v_cvt_pk_bf16_f32 v82, v100, v101
	v_cvt_pk_bf16_f32 v83, v102, v103
	v_cvt_pk_bf16_f32 v84, v154, v155
	v_cvt_pk_bf16_f32 v85, v156, v157
	v_cvt_pk_bf16_f32 v86, v158, v159
	v_cvt_pk_bf16_f32 v87, v160, v161
	v_cvt_pk_bf16_f32 v88, v104, v105
	v_cvt_pk_bf16_f32 v89, v106, v107
	v_cvt_pk_bf16_f32 v90, v108, v109
	v_cvt_pk_bf16_f32 v91, v110, v111
	v_cvt_pk_bf16_f32 v92, v162, v163
	v_cvt_pk_bf16_f32 v93, v164, v165
	v_cvt_pk_bf16_f32 v94, v166, v167
	v_cvt_pk_bf16_f32 v95, v168, v169
	s_branch .LBB0_304

; __device__ __forceinline__ void at_qk_half(const bool ONLINE, const bool act, const LAS unsigned char* kp, u32x4& pfa, u32x4& pfb, const char* pga, const char* pgb, const bf16x8 (&qf)[4], int q, int q0, int kbase, int hh, float& mrun, f32x16 (&O)[4], f32x16& L, bf16x8 (&pf)[4]) {
;     __builtin_amdgcn_s_setprio(3);
;     bf16x8 kf[8];
; #pragma unroll
;     for (int s = 0; s < 4; ++s) { kf[2 * s] = *(const LAS bf16x8*)(kp + 32 * s); kf[2 * s + 1] = *(const LAS bf16x8*)(kp + 32 * AT_ROWB + 32 * s); }
;     __builtin_amdgcn_sched_barrier(0);
;     pfa = *(const u32x4*)pga; pfb = *(const u32x4*)pgb;
;     __builtin_amdgcn_sched_barrier(0);
;     if (!act) { __builtin_amdgcn_s_setprio(0); return; }
;     f32x16 s0, s1;
; #pragma unroll
;     for (int i = 0; i < 16; ++i) { s0[i] = 0.f; s1[i] = 0.f; }
; #pragma unroll
;     for (int s = 0; s < 4; ++s) { s0 = MFMA32(kf[2 * s], qf[s], s0); s1 = MFMA32(kf[2 * s + 1], qf[s], s1); }
;     __builtin_amdgcn_s_setprio(0);
;     if (kbase + 63 > q0) {
;         const int kb = kbase + 4 * hh;
; #pragma unroll
;         for (int i = 0; i < 16; ++i) { const int kv = kb + (i & 3) + 8 * (i >> 2); if (kv > q) s0[i] = -INFINITY; if (kv + 32 > q) s1[i] = -INFINITY; }
;     }
;     if (ONLINE) {
; #pragma unroll
;         for (int i = 0; i < 16; ++i) { s0[i] -= mrun; s1[i] -= mrun; }
;         float mx = fmaxf(s0[0], s1[0]);
; #pragma unroll
;         for (int i = 1; i < 16; ++i) mx = at_max3(mx, s0[i], s1[i]);
;         mx = half_swap_max(mx);
;         if (__builtin_amdgcn_ballot_w64(mx > 8.f) != 0ull) {
;             const float d = fmaxf(mx, 0.f); const float alpha = __builtin_amdgcn_exp2f(-d); mrun += d;
; #pragma unroll
;             for (int e = 0; e < 4; ++e)
; __device__ __forceinline__ void attn_item(LAS unsigned char* lds, const bf16_t* Q, const bf16_t* Kb, const bf16_t* VT, bf16_t* aout, const float* subg, float lam, float omli, float kbound, int head, int qb) {
;     ...
;             const LAS unsigned char* stg = lds + (j & 1) * AT_KST; const int kbase = j * 64; const bool act = kbase <= qmax;
;             __builtin_amdgcn_s_setprio(3);
;             { const int jc_ = (j + 1) < ntm1 ? (j + 1) : ntm1; const size_t vo_ = (size_t)jc_ * 16384; const char* pga = bV0 + vo_ + voff; const char* pgb = bV1 + vo_ + voff;
;               at_qk_half(online, act, stg + kfo, vs0, vs1, pga, pgb, qf, q, q0, kbase, hh, mrun, O, L, pf); }
.LBB0_313:
	s_bitcmp1_b32 s53, 0
	s_cselect_b32 s0, 0x4800, 0
	s_add_i32 s54, s0, 0
	s_sub_i32 s55, s45, 63
	s_cmp_le_i32 s55, s40
	s_cselect_b64 s[0:1], -1, 0
	s_add_i32 s56, s53, 1
	s_min_i32 s58, s56, s41
	s_lshl_b64 s[60:61], s[58:59], 14
	s_cmp_gt_i32 s55, s40
	s_setprio 3
	v_lshl_add_u64 v[100:101], v[208:209], 0, s[60:61]
	v_lshl_add_u64 v[102:103], v[210:211], 0, s[60:61]
	v_add_u32_e32 v104, s54, v229
	s_setprio 3
	ds_read_b128 v[96:99], v104
	ds_read_b128 v[158:161], v104 offset:32
	ds_read_b128 v[154:157], v104 offset:64
	ds_read_b128 v[146:149], v104 offset:96
	ds_read_b128 v[170:173], v104 offset:4608
	ds_read_b128 v[162:165], v104 offset:4640
	ds_read_b128 v[166:169], v104 offset:4672
	ds_read_b128 v[150:153], v104 offset:4704
	global_load_dwordx4 v[138:141], v[100:101], off
	global_load_dwordx4 v[142:145], v[102:103], off
	s_cbranch_scc1 .LBB0_320
	s_cmp_le_i32 s45, s33
	s_cbranch_scc0 .Lmy_slow2
	s_andn2_b64 vcc, exec, s[64:65]
	s_cbranch_vccz .Lmy_slow2
	s_waitcnt lgkmcnt(7)
	v_mfma_f32_32x32x16_bf16 v[96:111], v[96:99], v[126:129], 0
	s_waitcnt lgkmcnt(6)
	v_mfma_f32_32x32x16_bf16 v[96:111], v[158:161], v[122:125], v[96:111]
	s_waitcnt lgkmcnt(5)
	v_mfma_f32_32x32x16_bf16 v[96:111], v[154:157], v[118:121], v[96:111]
	s_waitcnt lgkmcnt(4)
	v_mfma_f32_32x32x16_bf16 v[96:111], v[146:149], v[114:117], v[96:111]
	s_waitcnt lgkmcnt(3)
	v_mfma_f32_32x32x16_bf16 v[80:95], v[170:173], v[126:129], 0
	s_waitcnt lgkmcnt(2)
	v_mfma_f32_32x32x16_bf16 v[80:95], v[162:165], v[122:125], v[80:95]
	s_nop 8
	v_exp_f32_e32 v96, v96
	v_exp_f32_e32 v97, v97
	v_exp_f32_e32 v98, v98
	v_exp_f32_e32 v99, v99
	s_waitcnt lgkmcnt(1)
	v_mfma_f32_32x32x16_bf16 v[80:95], v[166:169], v[118:121], v[80:95]
	v_exp_f32_e32 v100, v100
	v_exp_f32_e32 v101, v101
	v_exp_f32_e32 v102, v102
	v_exp_f32_e32 v103, v103
	s_waitcnt lgkmcnt(0)
	v_mfma_f32_32x32x16_bf16 v[80:95], v[150:153], v[114:117], v[80:95]
	s_setprio 0
	v_exp_f32_e32 v104, v104
	v_exp_f32_e32 v105, v105
	v_exp_f32_e32 v106, v106
	v_exp_f32_e32 v107, v107
	v_exp_f32_e32 v108, v108
	v_exp_f32_e32 v109, v109
	v_exp_f32_e32 v110, v110
	v_exp_f32_e32 v111, v111
	s_nop 3
	v_exp_f32_e32 v146, v80
	v_exp_f32_e32 v147, v81
	v_exp_f32_e32 v148, v82
	v_exp_f32_e32 v149, v83
	v_exp_f32_e32 v150, v84
	v_exp_f32_e32 v151, v85
	v_exp_f32_e32 v152, v86
	v_exp_f32_e32 v153, v87
	v_exp_f32_e32 v154, v88
	v_exp_f32_e32 v155, v89
	v_exp_f32_e32 v156, v90
	v_exp_f32_e32 v157, v91
	v_exp_f32_e32 v158, v92
	v_exp_f32_e32 v159, v93
	v_exp_f32_e32 v160, v94
	v_exp_f32_e32 v161, v95
	v_cvt_pk_bf16_f32 v80, v96, v97
	v_cvt_pk_bf16_f32 v81, v98, v99
	v_cvt_pk_bf16_f32 v82, v100, v101
	v_cvt_pk_bf16_f32 v83, v102, v103
	v_cvt_pk_bf16_f32 v84, v146, v147
	v_cvt_pk_bf16_f32 v85, v148, v149
	v_cvt_pk_bf16_f32 v86, v150, v151
	v_cvt_pk_bf16_f32 v87, v152, v153
	v_cvt_pk_bf16_f32 v88, v104, v105
	v_cvt_pk_bf16_f32 v89, v106, v107
	v_cvt_pk_bf16_f32 v90, v108, v109
	v_cvt_pk_bf16_f32 v91, v110, v111
	v_cvt_pk_bf16_f32 v92, v154, v155
	v_cvt_pk_bf16_f32 v93, v156, v157
	v_cvt_pk_bf16_f32 v94, v158, v159
	v_cvt_pk_bf16_f32 v95, v160, v161
	s_branch .LBB0_320

; __device__ __forceinline__ void at_qk_half(const bool ONLINE, const bool act, const LAS unsigned char* kp, u32x4& pfa, u32x4& pfb, const char* pga, const char* pgb, const bf16x8 (&qf)[4], int q, int q0, int kbase, int hh, float& mrun, f32x16 (&O)[4], f32x16& L, bf16x8 (&pf)[4]) {
;     __builtin_amdgcn_s_setprio(3);
;     bf16x8 kf[8];
; #pragma unroll
;     for (int s = 0; s < 4; ++s) { kf[2 * s] = *(const LAS bf16x8*)(kp + 32 * s); kf[2 * s + 1] = *(const LAS bf16x8*)(kp + 32 * AT_ROWB + 32 * s); }
;     __builtin_amdgcn_sched_barrier(0);
;     pfa = *(const u32x4*)pga; pfb = *(const u32x4*)pgb;
;     __builtin_amdgcn_sched_barrier(0);
;     if (!act) { __builtin_amdgcn_s_setprio(0); return; }
;     f32x16 s0, s1;
; #pragma unroll
;     for (int i = 0; i < 16; ++i) { s0[i] = 0.f; s1[i] = 0.f; }
; #pragma unroll
;     for (int s = 0; s < 4; ++s) { s0 = MFMA32(kf[2 * s], qf[s], s0); s1 = MFMA32(kf[2 * s + 1], qf[s], s1); }
;     __builtin_amdgcn_s_setprio(0);
;     if (kbase + 63 > q0) {
;         const int kb = kbase + 4 * hh;
; #pragma unroll
;         for (int i = 0; i < 16; ++i) { const int kv = kb + (i & 3) + 8 * (i >> 2); if (kv > q) s0[i] = -INFINITY; if (kv + 32 > q) s1[i] = -INFINITY; }
;     }
;     if (ONLINE) {
; #pragma unroll
;         for (int i = 0; i < 16; ++i) { s0[i] -= mrun; s1[i] -= mrun; }
;         float mx = fmaxf(s0[0], s1[0]);
; #pragma unroll
;         for (int i = 1; i < 16; ++i) mx = at_max3(mx, s0[i], s1[i]);
;         mx = half_swap_max(mx);
;         if (__builtin_amdgcn_ballot_w64(mx > 8.f) != 0ull) {
;             const float d = fmaxf(mx, 0.f); const float alpha = __builtin_amdgcn_exp2f(-d); mrun += d;
; #pragma unroll
;             for (int e = 0; e < 4; ++e)
; #pragma unroll
;                 for (int i = 0; i < 16; ++i) O[e][i] *= alpha;
; __device__ __forceinline__ void attn_item(LAS unsigned char* lds, const bf16_t* Q, const bf16_t* Kb, const bf16_t* VT, bf16_t* aout, const float* subg, float lam, float omli, float kbound, int head, int qb) {
;     ...
;             __syncthreads();
;             __builtin_amdgcn_s_setprio(3);
;             { const int jc_ = (j + 2) < ntm1 ? (j + 2) : ntm1; const size_t ko_ = (size_t)jc_ * 8192; const char* pga = bK1 + ko_ + koff; const char* pgb = bK2 + ko_ + koff;
;               at_qk_half(online, kbase <= qmax, stg + kfo, ks0, ks1, pga, pgb, qf, q, q0, kbase, hh, mrun, O, L, pf); }
.Lmy_wj4:
	v_add_u32_e32 v232, s40, v212
	s_bitcmp1_b32 s39, 0
	s_cselect_b32 s42, 0x4800, 0
	s_sub_i32 s43, s1, 63
	s_waitcnt lgkmcnt(0)
	s_barrier
	s_setprio 3
	s_add_i32 s39, s39, 2
	s_min_i32 s58, s39, s22
	s_lshl_b64 s[40:41], s[58:59], 13
	v_lshl_add_u64 v[100:101], v[204:205], 0, s[40:41]
	v_lshl_add_u64 v[102:103], v[206:207], 0, s[40:41]
	s_cmp_gt_i32 s43, s21
	v_add_u32_e32 v104, s42, v230
	s_setprio 3
	ds_read_b128 v[96:99], v104
	ds_read_b128 v[166:169], v104 offset:32
	ds_read_b128 v[162:165], v104 offset:64
	ds_read_b128 v[154:157], v104 offset:96
	ds_read_b128 v[178:181], v104 offset:4608
	ds_read_b128 v[170:173], v104 offset:4640
	ds_read_b128 v[174:177], v104 offset:4672
	ds_read_b128 v[158:161], v104 offset:4704
	global_load_dwordx4 v[142:145], v[100:101], off
	global_load_dwordx4 v[138:141], v[102:103], off
	s_cbranch_scc1 .LBB0_342
	s_cmp_le_i32 s1, s33
	s_cbranch_scc0 .Lmy_slow3
	s_andn2_b64 vcc, exec, s[8:9]
	s_cbranch_vccz .Lmy_slow3
	s_waitcnt lgkmcnt(7)
	v_mfma_f32_32x32x16_bf16 v[96:111], v[96:99], v[126:129], 0
	s_waitcnt lgkmcnt(6)
	v_mfma_f32_32x32x16_bf16 v[96:111], v[166:169], v[122:125], v[96:111]
	s_waitcnt lgkmcnt(5)
	v_mfma_f32_32x32x16_bf16 v[96:111], v[162:165], v[118:121], v[96:111]
	s_waitcnt lgkmcnt(4)
	v_mfma_f32_32x32x16_bf16 v[96:111], v[154:157], v[114:117], v[96:111]
	s_waitcnt lgkmcnt(3)
	v_mfma_f32_32x32x16_bf16 v[80:95], v[178:181], v[126:129], 0
	s_waitcnt lgkmcnt(2)
	v_mfma_f32_32x32x16_bf16 v[80:95], v[170:173], v[122:125], v[80:95]
	s_nop 8
	v_exp_f32_e32 v96, v96
	v_exp_f32_e32 v97, v97
	v_exp_f32_e32 v98, v98
	v_exp_f32_e32 v99, v99
	s_waitcnt lgkmcnt(1)
	v_mfma_f32_32x32x16_bf16 v[80:95], v[174:177], v[118:121], v[80:95]
	v_exp_f32_e32 v100, v100
	v_exp_f32_e32 v101, v101
	v_exp_f32_e32 v102, v102
	v_exp_f32_e32 v103, v103
	s_waitcnt lgkmcnt(0)
	v_mfma_f32_32x32x16_bf16 v[80:95], v[158:161], v[114:117], v[80:95]
	s_setprio 0
	v_exp_f32_e32 v104, v104
	v_exp_f32_e32 v105, v105
	v_exp_f32_e32 v106, v106
	v_exp_f32_e32 v107, v107
	v_exp_f32_e32 v108, v108
	v_exp_f32_e32 v109, v109
	v_exp_f32_e32 v110, v110
	v_exp_f32_e32 v111, v111
	s_nop 3
	v_exp_f32_e32 v154, v80
	v_exp_f32_e32 v155, v81
	v_exp_f32_e32 v156, v82
	v_exp_f32_e32 v157, v83
	v_exp_f32_e32 v158, v84
	v_exp_f32_e32 v159, v85
	v_exp_f32_e32 v160, v86
	v_exp_f32_e32 v161, v87
	v_exp_f32_e32 v162, v88
	v_exp_f32_e32 v163, v89
	v_exp_f32_e32 v164, v90
	v_exp_f32_e32 v165, v91
	v_exp_f32_e32 v166, v92
	v_exp_f32_e32 v167, v93
	v_exp_f32_e32 v168, v94
	v_exp_f32_e32 v169, v95
	v_cvt_pk_bf16_f32 v80, v96, v97
	v_cvt_pk_bf16_f32 v81, v98, v99
	v_cvt_pk_bf16_f32 v82, v100, v101
	v_cvt_pk_bf16_f32 v83, v102, v103
	v_cvt_pk_bf16_f32 v84, v154, v155
	v_cvt_pk_bf16_f32 v85, v156, v157
	v_cvt_pk_bf16_f32 v86, v158, v159
	v_cvt_pk_bf16_f32 v87, v160, v161
	v_cvt_pk_bf16_f32 v88, v104, v105
	v_cvt_pk_bf16_f32 v89, v106, v107
	v_cvt_pk_bf16_f32 v90, v108, v109
	v_cvt_pk_bf16_f32 v91, v110, v111
	v_cvt_pk_bf16_f32 v92, v162, v163
	v_cvt_pk_bf16_f32 v93, v164, v165
	v_cvt_pk_bf16_f32 v94, v166, v167
	v_cvt_pk_bf16_f32 v95, v168, v169
	s_branch .LBB0_342

; __device__ __forceinline__ void at_qk_half(const bool ONLINE, const bool act, const LAS unsigned char* kp, u32x4& pfa, u32x4& pfb, const char* pga, const char* pgb, const bf16x8 (&qf)[4], int q, int q0, int kbase, int hh, float& mrun, f32x16 (&O)[4], f32x16& L, bf16x8 (&pf)[4]) {
;     __builtin_amdgcn_s_setprio(3);
;     bf16x8 kf[8];
; #pragma unroll
;     for (int s = 0; s < 4; ++s) { kf[2 * s] = *(const LAS bf16x8*)(kp + 32 * s); kf[2 * s + 1] = *(const LAS bf16x8*)(kp + 32 * AT_ROWB + 32 * s); }
;     __builtin_amdgcn_sched_barrier(0);
;     pfa = *(const u32x4*)pga; pfb = *(const u32x4*)pgb;
;     __builtin_amdgcn_sched_barrier(0);
;     if (!act) { __builtin_amdgcn_s_setprio(0); return; }
;     f32x16 s0, s1;
; #pragma unroll
;     for (int i = 0; i < 16; ++i) { s0[i] = 0.f; s1[i] = 0.f; }
; #pragma unroll
;     for (int s = 0; s < 4; ++s) { s0 = MFMA32(kf[2 * s], qf[s], s0); s1 = MFMA32(kf[2 * s + 1], qf[s], s1); }
;     __builtin_amdgcn_s_setprio(0);
;     if (kbase + 63 > q0) {
;         const int kb = kbase + 4 * hh;
; #pragma unroll
;         for (int i = 0; i < 16; ++i) { const int kv = kb + (i & 3) + 8 * (i >> 2); if (kv > q) s0[i] = -INFINITY; if (kv + 32 > q) s1[i] = -INFINITY; }
;     }
;     if (ONLINE) {
; #pragma unroll
;         for (int i = 0; i < 16; ++i) { s0[i] -= mrun; s1[i] -= mrun; }
;         float mx = fmaxf(s0[0], s1[0]);
; #pragma unroll
;         for (int i = 1; i < 16; ++i) mx = at_max3(mx, s0[i], s1[i]);
;         mx = half_swap_max(mx);
;         if (__builtin_amdgcn_ballot_w64(mx > 8.f) != 0ull) {
;             const float d = fmaxf(mx, 0.f); const float alpha = __builtin_amdgcn_exp2f(-d); mrun += d;
; #pragma unroll
;             for (int e = 0; e < 4; ++e)
; __device__ __forceinline__ void attn_item(LAS unsigned char* lds, const bf16_t* Q, const bf16_t* Kb, const bf16_t* VT, bf16_t* aout, const float* subg, float lam, float omli, float kbound, int head, int qb) {
;     ...
;             const LAS unsigned char* stg = lds + (j & 1) * AT_KST; const int kbase = j * 64; const bool act = kbase <= qmax;
;             __builtin_amdgcn_s_setprio(3);
;             { const int jc_ = (j + 1) < ntm1 ? (j + 1) : ntm1; const size_t vo_ = (size_t)jc_ * 16384; const char* pga = bV0 + vo_ + voff; const char* pgb = bV1 + vo_ + voff;
;               at_qk_half(online, act, stg + kfo, vs0, vs1, pga, pgb, qf, q, q0, kbase, hh, mrun, O, L, pf); }
.LBB0_351:
	s_bitcmp1_b32 s38, 0
	s_cselect_b32 s0, 0x4800, 0
	s_add_i32 s40, s0, 0
	s_sub_i32 s41, s20, 63
	s_cmp_le_i32 s41, s21
	s_cselect_b64 s[0:1], -1, 0
	s_add_i32 s39, s38, 1
	s_min_i32 s58, s39, s22
	s_lshl_b64 s[42:43], s[58:59], 14
	s_cmp_gt_i32 s41, s21
	s_setprio 3
	v_lshl_add_u64 v[100:101], v[208:209], 0, s[42:43]
	v_lshl_add_u64 v[102:103], v[210:211], 0, s[42:43]
	v_add_u32_e32 v104, s40, v229
	s_setprio 3
	ds_read_b128 v[96:99], v104
	ds_read_b128 v[158:161], v104 offset:32
	ds_read_b128 v[154:157], v104 offset:64
	ds_read_b128 v[146:149], v104 offset:96
	ds_read_b128 v[170:173], v104 offset:4608
	ds_read_b128 v[162:165], v104 offset:4640
	ds_read_b128 v[166:169], v104 offset:4672
	ds_read_b128 v[150:153], v104 offset:4704
	global_load_dwordx4 v[138:141], v[100:101], off
	global_load_dwordx4 v[142:145], v[102:103], off
	s_cbranch_scc1 .LBB0_358
	s_cmp_le_i32 s20, s33
	s_cbranch_scc0 .Lmy_slow4
	s_andn2_b64 vcc, exec, s[8:9]
	s_cbranch_vccz .Lmy_slow4
	s_waitcnt lgkmcnt(7)
	v_mfma_f32_32x32x16_bf16 v[96:111], v[96:99], v[126:129], 0
	s_waitcnt lgkmcnt(6)
	v_mfma_f32_32x32x16_bf16 v[96:111], v[158:161], v[122:125], v[96:111]
	s_waitcnt lgkmcnt(5)
	v_mfma_f32_32x32x16_bf16 v[96:111], v[154:157], v[118:121], v[96:111]
	s_waitcnt lgkmcnt(4)
	v_mfma_f32_32x32x16_bf16 v[96:111], v[146:149], v[114:117], v[96:111]
	s_waitcnt lgkmcnt(3)
	v_mfma_f32_32x32x16_bf16 v[80:95], v[170:173], v[126:129], 0
	s_waitcnt lgkmcnt(2)
	v_mfma_f32_32x32x16_bf16 v[80:95], v[162:165], v[122:125], v[80:95]
	s_nop 8
	v_exp_f32_e32 v96, v96
	v_exp_f32_e32 v97, v97
	v_exp_f32_e32 v98, v98
	v_exp_f32_e32 v99, v99
	s_waitcnt lgkmcnt(1)
	v_mfma_f32_32x32x16_bf16 v[80:95], v[166:169], v[118:121], v[80:95]
	v_exp_f32_e32 v100, v100
	v_exp_f32_e32 v101, v101
	v_exp_f32_e32 v102, v102
	v_exp_f32_e32 v103, v103
	s_waitcnt lgkmcnt(0)
	v_mfma_f32_32x32x16_bf16 v[80:95], v[150:153], v[114:117], v[80:95]
	s_setprio 0
	v_exp_f32_e32 v104, v104
	v_exp_f32_e32 v105, v105
	v_exp_f32_e32 v106, v106
	v_exp_f32_e32 v107, v107
	v_exp_f32_e32 v108, v108
	v_exp_f32_e32 v109, v109
	v_exp_f32_e32 v110, v110
	v_exp_f32_e32 v111, v111
	s_nop 3
	v_exp_f32_e32 v146, v80
	v_exp_f32_e32 v147, v81
	v_exp_f32_e32 v148, v82
	v_exp_f32_e32 v149, v83
	v_exp_f32_e32 v150, v84
	v_exp_f32_e32 v151, v85
	v_exp_f32_e32 v152, v86
	v_exp_f32_e32 v153, v87
	v_exp_f32_e32 v154, v88
	v_exp_f32_e32 v155, v89
	v_exp_f32_e32 v156, v90
	v_exp_f32_e32 v157, v91
	v_exp_f32_e32 v158, v92
	v_exp_f32_e32 v159, v93
	v_exp_f32_e32 v160, v94
	v_exp_f32_e32 v161, v95
	v_cvt_pk_bf16_f32 v80, v96, v97
	v_cvt_pk_bf16_f32 v81, v98, v99
	v_cvt_pk_bf16_f32 v82, v100, v101
	v_cvt_pk_bf16_f32 v83, v102, v103
	v_cvt_pk_bf16_f32 v84, v146, v147
	v_cvt_pk_bf16_f32 v85, v148, v149
	v_cvt_pk_bf16_f32 v86, v150, v151
	v_cvt_pk_bf16_f32 v87, v152, v153
	v_cvt_pk_bf16_f32 v88, v104, v105
	v_cvt_pk_bf16_f32 v89, v106, v107
	v_cvt_pk_bf16_f32 v90, v108, v109
	v_cvt_pk_bf16_f32 v91, v110, v111
	v_cvt_pk_bf16_f32 v92, v154, v155
	v_cvt_pk_bf16_f32 v93, v156, v157
	v_cvt_pk_bf16_f32 v94, v158, v159
	v_cvt_pk_bf16_f32 v95, v160, v161
	s_branch .LBB0_358
